# grid barrier: all workgroups poll the cross-XCD arrival counter (no returning atomic, no separate release word, no relay)
# speedup vs baseline: 1.0102x; 1.0052x over previous
.LBB0_69:
	s_or_b64 exec, exec, s[10:11]
	v_cvt_f32_u32_e32 v4, v2
	s_waitcnt vmcnt(0)
	v_readfirstlane_b32 s6, v3
	v_sub_u32_e32 v3, 0, v2
	v_rcp_iflag_f32_e32 v4, v4
	v_add_u32_e32 v5, s6, v1
	v_mul_f32_e32 v4, 0x4f7ffffe, v4
	v_cvt_u32_f32_e32 v4, v4
	v_mul_lo_u32 v1, v3, v4
	v_mul_hi_u32 v1, v4, v1
	v_add_u32_e32 v1, v4, v1
	v_mul_hi_u32 v1, v5, v1
	v_mul_lo_u32 v3, v1, v2
	v_sub_u32_e32 v3, v5, v3
	v_add_u32_e32 v4, 1, v1
	v_cmp_ge_u32_e32 vcc, v3, v2
	s_nop 1
	v_cndmask_b32_e32 v1, v1, v4, vcc
	v_sub_u32_e32 v4, v3, v2
	v_cndmask_b32_e32 v3, v3, v4, vcc
	v_add_u32_e32 v4, 1, v1
	v_cmp_ge_u32_e32 vcc, v3, v2
	v_add_u32_e32 v3, 1, v5
	s_nop 0
	v_cndmask_b32_e32 v1, v1, v4, vcc
	v_mul_lo_u32 v4, v2, v1
	v_add_u32_e32 v2, v4, v2
	v_cmp_ne_u32_e32 vcc, v3, v2
	s_waitcnt lgkmcnt(0)
	v_add_u32_e32 v2, 1, v1
	v_mul_lo_u32 v2, v2, v0
	v_mov_b32_e32 v3, 0x3b000
	s_cbranch_vccnz .Lxb_poll_0
	buffer_wbl2 sc1
	s_waitcnt vmcnt(0)
	v_mov_b32_e32 v4, 1
	global_atomic_add v3, v4, s[30:31] offset:1024
.Lxb_poll_0:
	s_mov_b32 s26, 0
.Lxb_spin_0:
	global_load_dword v4, v3, s[30:31] offset:1024 sc1
	s_add_i32 s26, s26, 1
	s_waitcnt vmcnt(0)
	v_sub_u32_e32 v4, v4, v2
	v_cmp_le_i32_e32 vcc, 0, v4
	s_cbranch_vccnz .Lxb_done_0
	s_sleep 1
	s_and_b32 s22, s26, 0xff
	s_cmp_lg_u32 s22, 0
	s_cbranch_scc1 .Lxb_spin_0
	v_mov_b32_e32 v5, 0x38200
	global_load_dword v4, v5, s[30:31] sc1
	s_waitcnt vmcnt(0)
	v_cmp_ne_u32_e32 vcc, 0, v4
	s_cbranch_vccnz .Lxb_done_0
	s_cmp_lt_u32 s26, 0x4000
	s_cbranch_scc1 .Lxb_spin_0
	v_mov_b32_e32 v4, 1
	global_atomic_add v5, v4, s[30:31]
	s_waitcnt vmcnt(0)
.Lxb_done_0:
.LBB0_103:
	s_or_b64 exec, exec, s[0:1]
	s_waitcnt lgkmcnt(0)
	s_barrier

.LBB0_411:
	s_or_b64 exec, exec, s[6:7]
	v_cvt_f32_u32_e32 v4, v2
	s_waitcnt vmcnt(0)
	v_readfirstlane_b32 s4, v3
	v_sub_u32_e32 v3, 0, v2
	v_rcp_iflag_f32_e32 v4, v4
	v_add_u32_e32 v5, s4, v1
	v_mul_f32_e32 v4, 0x4f7ffffe, v4
	v_cvt_u32_f32_e32 v4, v4
	v_mul_lo_u32 v1, v3, v4
	v_mul_hi_u32 v1, v4, v1
	v_add_u32_e32 v1, v4, v1
	v_mul_hi_u32 v1, v5, v1
	v_mul_lo_u32 v3, v1, v2
	v_sub_u32_e32 v3, v5, v3
	v_add_u32_e32 v4, 1, v1
	v_cmp_ge_u32_e32 vcc, v3, v2
	s_nop 1
	v_cndmask_b32_e32 v1, v1, v4, vcc
	v_sub_u32_e32 v4, v3, v2
	v_cndmask_b32_e32 v3, v3, v4, vcc
	v_add_u32_e32 v4, 1, v1
	v_cmp_ge_u32_e32 vcc, v3, v2
	v_add_u32_e32 v3, 1, v5
	s_nop 0
	v_cndmask_b32_e32 v1, v1, v4, vcc
	v_mul_lo_u32 v4, v2, v1
	v_add_u32_e32 v2, v4, v2
	v_cmp_ne_u32_e32 vcc, v3, v2
	s_waitcnt lgkmcnt(0)
	v_add_u32_e32 v2, 1, v1
	v_mul_lo_u32 v2, v2, v0
	v_mov_b32_e32 v3, 0x3b000
	s_cbranch_vccnz .Lxb_poll_3
	buffer_wbl2 sc1
	s_waitcnt vmcnt(0)
	v_mov_b32_e32 v4, 1
	global_atomic_add v3, v4, s[30:31] offset:1024
.Lxb_poll_3:
	s_mov_b32 s24, 0
.Lxb_spin_3:
	global_load_dword v4, v3, s[30:31] offset:1024 sc1
	s_add_i32 s24, s24, 1
	s_waitcnt vmcnt(0)
	v_sub_u32_e32 v4, v4, v2
	v_cmp_le_i32_e32 vcc, 0, v4
	s_cbranch_vccnz .Lxb_done_3
	s_sleep 1
	s_and_b32 s20, s24, 0xff
	s_cmp_lg_u32 s20, 0
	s_cbranch_scc1 .Lxb_spin_3
	v_mov_b32_e32 v5, 0x38200
	global_load_dword v4, v5, s[30:31] sc1
	s_waitcnt vmcnt(0)
	v_cmp_ne_u32_e32 vcc, 0, v4
	s_cbranch_vccnz .Lxb_done_3
	s_cmp_lt_u32 s24, 0x4000
	s_cbranch_scc1 .Lxb_spin_3
	v_mov_b32_e32 v4, 1
	global_atomic_add v5, v4, s[30:31]
	s_waitcnt vmcnt(0)
